# v27: add P1 sample-tail w_in row prefetch before the A-fill (on top of p6tail/p7tail prefetch stack)
# baseline (speedup 1.0000x reference)
.LBB0_545:
	v_readlane_b32 s99, v254, 3
	v_and_b32_e32 v142, 15, v0
	s_lshl_b32 s100, s84, 9
	v_and_b32_e32 v144, 48, v212
	v_mov_b32_e32 v145, 0
	s_add_u32 s100, s82, s100
	s_addc_u32 s101, s83, 0
	v_lshl_or_b32 v142, s99, 4, v142
	v_lshl_add_u64 v[144:145], s[100:101], 0, v[144:145]
	s_mov_b64 s[100:101], 0x200000
	v_ashrrev_i32_e32 v143, 31, v142
	v_lshl_add_u64 v[144:145], v[144:145], 0, s[100:101]
	v_lshlrev_b64 v[146:147], 12, v[142:143]
	v_lshl_add_u64 v[146:147], v[144:145], 0, v[146:147]
	global_load_dwordx4 v[74:77], v[146:147], off
	global_load_dwordx4 v[78:81], v[146:147], off offset:64
	global_load_dwordx4 v[82:85], v[146:147], off offset:128
	global_load_dwordx4 v[86:89], v[146:147], off offset:192
	global_load_dwordx4 v[90:93], v[146:147], off offset:256
	global_load_dwordx4 v[94:97], v[146:147], off offset:320
	global_load_dwordx4 v[98:101], v[146:147], off offset:384
	global_load_dwordx4 v[102:105], v[146:147], off offset:448
	v_readlane_b32 s100, v254, 2
	s_nop 3
	s_add_i32 s101, s99, s100
	s_cmpk_lt_i32 s101, 0x161
	s_cbranch_scc0 .Lp1t_no2
	s_lshl_b32 s100, s100, 4
	v_add_u32_e32 v142, s100, v142
	v_ashrrev_i32_e32 v143, 31, v142
	v_lshlrev_b64 v[146:147], 12, v[142:143]
	v_lshl_add_u64 v[146:147], v[144:145], 0, v[146:147]
	global_load_dwordx4 v[106:109], v[146:147], off
	global_load_dwordx4 v[110:113], v[146:147], off offset:64
	global_load_dwordx4 v[114:117], v[146:147], off offset:128
	global_load_dwordx4 v[118:121], v[146:147], off offset:192
	global_load_dwordx4 v[122:125], v[146:147], off offset:256
	global_load_dwordx4 v[126:129], v[146:147], off offset:320
	global_load_dwordx4 v[130:133], v[146:147], off offset:384
	global_load_dwordx4 v[134:137], v[146:147], off offset:448
.Lp1t_no2:
	s_mov_b32 s98, 0
	v_readlane_b32 s56, v254, 9
	v_readlane_b32 s57, v254, 10
	s_mov_b32 s85, 0
	v_readlane_b32 s58, v254, 11
	v_readlane_b32 s59, v254, 12
	s_mov_b64 s[12:13], s[56:57]
	s_lshl_b64 s[0:1], s[84:85], 13
	s_mov_b64 s[14:15], s[58:59]
	s_add_u32 s0, s14, s0
	s_addc_u32 s1, s15, s1
	v_lshlrev_b32_e32 v40, 4, v212
	global_load_dwordx4 v[30:33], v40, s[0:1]
	global_load_dwordx4 v[26:29], v40, s[0:1] offset:1024
	global_load_dwordx4 v[22:25], v40, s[0:1] offset:2048
	global_load_dwordx4 v[18:21], v40, s[0:1] offset:3072
	v_mov_b32_e32 v41, 0
	s_movk_i32 s2, 0x1000
	s_waitcnt vmcnt(15)
	v_lshl_add_u64 v[2:3], s[0:1], 0, v[40:41]
	s_waitcnt vmcnt(14)
	v_add_co_u32_e32 v6, vcc, s2, v2
	v_mbcnt_lo_u32_b32 v35, -1, 0
	s_nop 0
	v_addc_co_u32_e32 v7, vcc, 0, v3, vcc
	global_load_dwordx4 v[14:17], v[6:7], off
	global_load_dwordx4 v[10:13], v[6:7], off offset:1024
	global_load_dwordx4 v[2:5], v[6:7], off offset:3072
	s_nop 0
	global_load_dwordx4 v[6:9], v[6:7], off offset:2048
	v_mbcnt_hi_u32_b32 v35, -1, v35
	v_and_b32_e32 v36, 64, v35
	v_xor_b32_e32 v37, 1, v35
	v_add_u32_e32 v58, 64, v36
	v_cmp_lt_i32_e32 vcc, v37, v58
	v_readlane_b32 s0, v254, 25
	v_readlane_b32 s2, v254, 27
	v_cndmask_b32_e32 v36, v35, v37, vcc
	v_lshlrev_b32_e32 v59, 2, v36
	v_readlane_b32 s3, v254, 28
	v_readlane_b32 s12, v254, 37
	v_readlane_b32 s13, v254, 38
	v_readlane_b32 s14, v254, 39
	v_readlane_b32 s15, v254, 40
	v_readlane_b32 s1, v254, 26
	s_mov_b64 s[14:15], s[2:3]
	v_lshl_add_u64 v[42:43], s[14:15], 0, v[40:41]
	v_xor_b32_e32 v41, 2, v35
	v_cmp_lt_i32_e32 vcc, v41, v58
	s_cmp_lg_u64 s[14:15], 0
	v_mov_b32_e32 v34, 1.0
	s_mov_b64 s[12:13], s[0:1]
	s_cselect_b64 s[2:3], -1, 0
	s_cmp_eq_u64 s[14:15], 0
	v_readlane_b32 s60, v254, 13
	v_readlane_b32 s61, v254, 14
	v_readlane_b32 s62, v254, 15
	v_readlane_b32 s63, v254, 16
	v_readlane_b32 s64, v254, 17
	v_readlane_b32 s65, v254, 18
	v_readlane_b32 s66, v254, 19
	v_readlane_b32 s67, v254, 20
	v_readlane_b32 s68, v254, 21
	v_readlane_b32 s69, v254, 22
	v_readlane_b32 s70, v254, 23
	v_readlane_b32 s71, v254, 24
	v_readlane_b32 s4, v254, 29
	v_readlane_b32 s5, v254, 30
	v_readlane_b32 s6, v254, 31
	v_readlane_b32 s7, v254, 32
	v_readlane_b32 s8, v254, 33
	v_readlane_b32 s9, v254, 34
	v_readlane_b32 s10, v254, 35
	v_readlane_b32 s11, v254, 36
	s_waitcnt vmcnt(7)
	v_mov_b32_e32 v38, v31
	s_waitcnt vmcnt(6)
	v_mov_b32_e32 v39, v27
	v_mov_b32_e32 v46, v33
	v_mov_b32_e32 v47, v29
	v_mov_b32_e32 v36, v30
	v_mov_b32_e32 v37, v26
	v_mov_b32_e32 v44, v32
	v_mov_b32_e32 v45, v28
	s_waitcnt vmcnt(5)
	v_pk_mul_f32 v[48:49], v[24:25], v[24:25]
	v_pk_mul_f32 v[50:51], v[22:23], v[22:23]
	v_pk_mul_f32 v[38:39], v[38:39], v[38:39]
	v_pk_mul_f32 v[46:47], v[46:47], v[46:47]
	v_pk_mov_b32 v[56:57], v[50:51], v[48:49] op_sel:[1,0]
	v_mov_b32_e32 v51, v49
	v_pk_fma_f32 v[36:37], v[36:37], v[36:37], v[38:39]
	v_pk_fma_f32 v[38:39], v[44:45], v[44:45], v[46:47]
	s_waitcnt vmcnt(4)
	v_mul_f32_e32 v52, v19, v19
	v_mul_f32_e32 v54, v21, v21
	v_pk_add_f32 v[44:45], v[56:57], v[50:51]
	v_pk_add_f32 v[36:37], v[36:37], v[38:39]
	v_pk_fma_f32 v[48:49], v[18:19], v[18:19], v[52:53] op_sel_hi:[1,1,0]
	v_pk_fma_f32 v[52:53], v[20:21], v[20:21], v[54:55] op_sel_hi:[1,1,0]
	s_waitcnt vmcnt(3)
	v_mul_f32_e32 v57, v14, v14
	v_mul_f32_e32 v60, v15, v15
	v_pk_add_f32 v[38:39], v[44:45], v[44:45] op_sel:[0,1] op_sel_hi:[1,0]
	v_pk_add_f32 v[36:37], v[36:37], v[36:37] op_sel:[0,1] op_sel_hi:[1,0]
	v_mul_f32_e32 v49, v16, v16
	v_mul_f32_e32 v53, v17, v17
	s_waitcnt vmcnt(2)
	v_pk_mul_f32 v[46:47], v[12:13], v[12:13]
	v_pk_mul_f32 v[50:51], v[10:11], v[10:11]
	v_mov_b32_e32 v39, v60
	v_mov_b32_e32 v37, v57
	v_pk_mov_b32 v[44:45], v[50:51], v[46:47] op_sel:[1,0]
	v_mov_b32_e32 v51, v47
	v_pk_add_f32 v[48:49], v[48:49], v[52:53]
	v_pk_add_f32 v[36:37], v[36:37], v[38:39]
	s_waitcnt vmcnt(0)
	v_mul_f32_e32 v54, v7, v7
	v_mul_f32_e32 v56, v9, v9
	v_pk_add_f32 v[44:45], v[44:45], v[50:51]
	v_pk_add_f32 v[36:37], v[36:37], v[48:49]
	v_mul_f32_e32 v61, v2, v2
	v_mul_f32_e32 v62, v3, v3
	v_mul_f32_e32 v63, v4, v4
	v_mul_f32_e32 v64, v5, v5
	v_pk_fma_f32 v[46:47], v[6:7], v[6:7], v[54:55] op_sel_hi:[1,1,0]
	v_pk_fma_f32 v[54:55], v[8:9], v[8:9], v[56:57] op_sel_hi:[1,1,0]
	v_pk_add_f32 v[44:45], v[44:45], v[44:45] op_sel:[0,1] op_sel_hi:[1,0]
	v_pk_add_f32 v[36:37], v[36:37], v[36:37] op_sel:[0,1] op_sel_hi:[1,0]
	v_mov_b32_e32 v47, v63
	v_mov_b32_e32 v55, v64
	v_mov_b32_e32 v45, v62
	v_mov_b32_e32 v37, v61
	v_pk_add_f32 v[46:47], v[46:47], v[54:55]
	v_pk_add_f32 v[36:37], v[36:37], v[44:45]
	v_cndmask_b32_e32 v39, v35, v41, vcc
	v_pk_add_f32 v[36:37], v[36:37], v[46:47]
	v_lshlrev_b32_e32 v39, 2, v39
	v_add_f32_e32 v36, v36, v37
	ds_bpermute_b32 v37, v59, v36
	v_xor_b32_e32 v38, 4, v35
	v_cmp_lt_i32_e32 vcc, v38, v58
	s_waitcnt lgkmcnt(0)
	v_add_f32_e32 v36, v36, v37
	ds_bpermute_b32 v37, v39, v36
	v_cndmask_b32_e32 v38, v35, v38, vcc
	v_lshlrev_b32_e32 v38, 2, v38
	v_xor_b32_e32 v39, 8, v35
	v_cmp_lt_i32_e32 vcc, v39, v58
	s_waitcnt lgkmcnt(0)
	v_add_f32_e32 v36, v36, v37
	ds_bpermute_b32 v37, v38, v36
	v_cndmask_b32_e32 v39, v35, v39, vcc
	v_lshlrev_b32_e32 v39, 2, v39
	v_xor_b32_e32 v38, 16, v35
	v_cmp_lt_i32_e32 vcc, v38, v58
	s_waitcnt lgkmcnt(0)
	v_add_f32_e32 v36, v36, v37
	ds_bpermute_b32 v37, v39, v36
	v_cndmask_b32_e32 v38, v35, v38, vcc
	v_lshlrev_b32_e32 v38, 2, v38
	v_xor_b32_e32 v39, 32, v35
	v_cmp_lt_i32_e32 vcc, v39, v58
	s_waitcnt lgkmcnt(0)
	v_add_f32_e32 v36, v36, v37
	ds_bpermute_b32 v37, v38, v36
	v_cndmask_b32_e32 v35, v35, v39, vcc
	v_lshlrev_b32_e32 v38, 2, v35
	v_mov_b32_e32 v39, 1.0
	s_waitcnt lgkmcnt(0)
	v_add_f32_e32 v35, v36, v37
	ds_bpermute_b32 v41, v38, v35
	v_mov_b32_e32 v36, 1.0
	v_mov_b32_e32 v37, 1.0
	v_mov_b32_e32 v38, 1.0
	s_cbranch_scc1 .Lp1fill_gnull
	global_load_dwordx4 v[36:39], v[42:43], off
	global_load_dwordx4 v[46:49], v[42:43], off offset:1024
	global_load_dwordx4 v[50:53], v[42:43], off offset:2048
	global_load_dwordx4 v[54:57], v[42:43], off offset:3072
	v_add_co_u32_e32 v72, vcc, 0x1000, v42
	s_nop 1
	v_addc_co_u32_e32 v73, vcc, 0, v43, vcc
	global_load_dwordx4 v[58:61], v[72:73], off
	global_load_dwordx4 v[62:65], v[72:73], off offset:1024
	global_load_dwordx4 v[66:69], v[72:73], off offset:2048
	global_load_dwordx4 v[70:73], v[72:73], off offset:3072
	s_branch .LBB0_547

.LBB0_564:
	s_cmp_eq_u32 s98, 0
	s_cbranch_scc1 .Lp1t_w0
	s_cmp_eq_u32 s98, 1
	s_cbranch_scc1 .Lp1t_w1
	v_add_u32_e32 v2, s14, v160
	v_ashrrev_i32_e32 v3, 31, v2
	v_lshlrev_b64 v[2:3], 12, v[2:3]
	v_lshl_add_u64 v[38:39], v[8:9], 0, v[2:3]
	global_load_dwordx4 v[2:5], v[38:39], off
	global_load_dwordx4 v[14:17], v[38:39], off offset:64
	global_load_dwordx4 v[18:21], v[38:39], off offset:128
	global_load_dwordx4 v[22:25], v[38:39], off offset:192
	global_load_dwordx4 v[26:29], v[38:39], off offset:256
	global_load_dwordx4 v[30:33], v[38:39], off offset:320
	global_load_dwordx4 v[34:37], v[38:39], off offset:384
	s_nop 0
	global_load_dwordx4 v[38:41], v[38:39], off offset:448
	s_branch .Lp1t_go

.Lp1t_w1:
	s_waitcnt vmcnt(0)
	v_mov_b64_e32 v[2:3], v[106:107]
	v_mov_b64_e32 v[4:5], v[108:109]
	v_mov_b64_e32 v[14:15], v[110:111]
	v_mov_b64_e32 v[16:17], v[112:113]
	v_mov_b64_e32 v[18:19], v[114:115]
	v_mov_b64_e32 v[20:21], v[116:117]
	v_mov_b64_e32 v[22:23], v[118:119]
	v_mov_b64_e32 v[24:25], v[120:121]
	v_mov_b64_e32 v[26:27], v[122:123]
	v_mov_b64_e32 v[28:29], v[124:125]
	v_mov_b64_e32 v[30:31], v[126:127]
	v_mov_b64_e32 v[32:33], v[128:129]
	v_mov_b64_e32 v[34:35], v[130:131]
	v_mov_b64_e32 v[36:37], v[132:133]
	v_mov_b64_e32 v[38:39], v[134:135]
	v_mov_b64_e32 v[40:41], v[136:137]
.Lp1t_go:
	s_add_i32 s98, s98, 1
	ds_read_b128 v[42:45], v12
	ds_read_b128 v[46:49], v12 offset:64
	ds_read_b128 v[50:53], v12 offset:128
	ds_read_b128 v[54:57], v12 offset:192
	ds_read_b128 v[58:61], v12 offset:256
	ds_read_b128 v[62:65], v12 offset:320
	ds_read_b128 v[66:69], v12 offset:384
	ds_read_b128 v[70:73], v12 offset:448
	s_waitcnt lgkmcnt(7)
	v_cndmask_b32_e64 v45, v45, 0, s[0:1]
	v_cndmask_b32_e64 v44, v44, 0, s[0:1]
	v_cndmask_b32_e64 v43, v43, 0, s[0:1]
	v_cndmask_b32_e64 v42, v42, 0, s[0:1]
	s_waitcnt lgkmcnt(6)
	v_cndmask_b32_e64 v49, v49, 0, s[0:1]
	v_cndmask_b32_e64 v48, v48, 0, s[0:1]
	v_cndmask_b32_e64 v47, v47, 0, s[0:1]
	v_cndmask_b32_e64 v46, v46, 0, s[0:1]
	s_waitcnt lgkmcnt(5)
	v_cndmask_b32_e64 v53, v53, 0, s[0:1]
	v_cndmask_b32_e64 v52, v52, 0, s[0:1]
	v_cndmask_b32_e64 v51, v51, 0, s[0:1]
	v_cndmask_b32_e64 v50, v50, 0, s[0:1]
	s_waitcnt lgkmcnt(4)
	v_cndmask_b32_e64 v57, v57, 0, s[0:1]
	v_cndmask_b32_e64 v56, v56, 0, s[0:1]
	v_cndmask_b32_e64 v55, v55, 0, s[0:1]
	v_cndmask_b32_e64 v54, v54, 0, s[0:1]
	s_waitcnt vmcnt(7)
	v_mfma_f32_16x16x32_bf16 v[2:5], v[42:45], v[2:5], 0
	s_waitcnt vmcnt(6)
	v_mfma_f32_16x16x32_bf16 v[2:5], v[46:49], v[14:17], v[2:5]
	s_waitcnt lgkmcnt(3)
	v_cndmask_b32_e64 v17, v61, 0, s[0:1]
	v_cndmask_b32_e64 v16, v60, 0, s[0:1]
	v_cndmask_b32_e64 v15, v59, 0, s[0:1]
	s_waitcnt vmcnt(5)
	v_mfma_f32_16x16x32_bf16 v[2:5], v[50:53], v[18:21], v[2:5]
	v_cndmask_b32_e64 v14, v58, 0, s[0:1]
	s_waitcnt lgkmcnt(2)
	v_cndmask_b32_e64 v21, v65, 0, s[0:1]
	v_cndmask_b32_e64 v20, v64, 0, s[0:1]
	s_waitcnt vmcnt(4)
	v_mfma_f32_16x16x32_bf16 v[2:5], v[54:57], v[22:25], v[2:5]
	v_cndmask_b32_e64 v19, v63, 0, s[0:1]
	v_cndmask_b32_e64 v18, v62, 0, s[0:1]
	s_waitcnt lgkmcnt(1)
	v_cndmask_b32_e64 v25, v69, 0, s[0:1]
	s_waitcnt vmcnt(3)
	v_mfma_f32_16x16x32_bf16 v[2:5], v[14:17], v[26:29], v[2:5]
	v_cndmask_b32_e64 v24, v68, 0, s[0:1]
	v_cndmask_b32_e64 v23, v67, 0, s[0:1]
	v_cndmask_b32_e64 v22, v66, 0, s[0:1]
	s_waitcnt vmcnt(2)
	v_mfma_f32_16x16x32_bf16 v[2:5], v[18:21], v[30:33], v[2:5]
	s_waitcnt lgkmcnt(0)
	v_cndmask_b32_e64 v17, v73, 0, s[0:1]
	v_cndmask_b32_e64 v16, v72, 0, s[0:1]
	v_cndmask_b32_e64 v15, v71, 0, s[0:1]
	v_cndmask_b32_e64 v14, v70, 0, s[0:1]
	s_waitcnt vmcnt(1)
	v_mfma_f32_16x16x32_bf16 v[2:5], v[22:25], v[34:37], v[2:5]
	s_waitcnt vmcnt(0)
	v_mfma_f32_16x16x32_bf16 v[2:5], v[14:17], v[38:41], v[2:5]
	s_and_saveexec_b64 s[2:3], s[4:5]
	s_cbranch_execz .LBB0_566
	v_add_u32_e32 v6, 0x8000, v13
	s_nop 4
	ds_write2_b32 v6, v2, v3 offset0:128 offset1:144
	ds_write2_b32 v6, v4, v5 offset0:160 offset1:176
